# attention: one static s_setprio 1 for waves 0-3 for the whole attention phase (other half of the doc 6.3 recipe), reset to 0 after
# speedup vs baseline: 1.0076x; 1.0021x over previous
.LBB0_410:
	s_lshl_b32 s82, s75, 17
	v_readlane_b32 s0, v245, 0
	s_bitcmp1_b32 s0, 2
	v_and_b32_e32 v228, 63, v0
	v_writelane_b32 v245, s66, 14
	s_nop 1
	v_writelane_b32 v245, s67, 15
	s_cbranch_scc1 .LBB0_519
	v_readfirstlane_b32 s0, v0
	s_nop 3
	s_and_b32 s0, s0, 0x3ff
	s_lshr_b32 s0, s0, 6
	s_cmp_lt_u32 s0, 4
	s_cbranch_scc0 .Lattn_prio_done
	s_setprio 1
